# combo1 plus non-temporal (nt) loads for the once-read f32 weights, x and mem in the conversion prologue
# speedup vs baseline: 1.0198x; 1.0198x over previous
.LBB0_82:
	s_lshl_b32 s38, s74, 6
	v_or_b32_e32 v2, s38, v75
	s_ashr_i32 s39, s38, 31
	s_mul_i32 s74, s39, s51
	v_mad_u64_u32 v[2:3], s[40:41], v2, s51, 0
	v_add_u32_e32 v3, s74, v3
	v_cmp_lt_i32_e32 vcc, -1, v4
	v_lshl_add_u64 v[2:3], v[2:3], 2, s[0:1]
	v_mov_b32_e32 v6, 0
	v_cndmask_b32_e32 v66, 0, v4, vcc
	v_lshl_add_u64 v[72:73], v[66:67], 2, v[2:3]
	v_mov_b32_e32 v2, 0
	v_mov_b32_e32 v7, 0
	v_mov_b32_e32 v8, 0
	v_mov_b32_e32 v9, 0
	s_and_saveexec_b64 s[40:41], vcc
	s_cbranch_execz .LBB0_84
	global_load_dwordx4 v[6:9], v[72:73], off nt
.LBB0_84:
	s_or_b64 exec, exec, s[40:41]
	v_mov_b32_e32 v3, 0
	v_mov_b32_e32 v4, 0
	v_mov_b32_e32 v5, 0
	s_and_saveexec_b64 s[40:41], vcc
	s_cbranch_execz .LBB0_86
	v_lshl_add_u64 v[2:3], s[4:5], 2, v[72:73]
	global_load_dwordx4 v[2:5], v[2:3], off nt
.LBB0_86:
	s_or_b64 exec, exec, s[40:41]
	v_mov_b32_e32 v10, 0
	v_mov_b32_e32 v14, 0
	v_mov_b32_e32 v15, 0
	v_mov_b32_e32 v16, 0
	v_mov_b32_e32 v17, 0
	s_and_saveexec_b64 s[40:41], vcc
	s_cbranch_execz .LBB0_88
	v_lshl_add_u64 v[12:13], s[6:7], 2, v[72:73]
	global_load_dwordx4 v[14:17], v[12:13], off nt
.LBB0_88:
	s_or_b64 exec, exec, s[40:41]
	v_mov_b32_e32 v11, 0
	v_mov_b32_e32 v12, 0
	v_mov_b32_e32 v13, 0
	s_and_saveexec_b64 s[40:41], vcc
	s_cbranch_execz .LBB0_90
	v_lshl_add_u64 v[10:11], s[8:9], 2, v[72:73]
	global_load_dwordx4 v[10:13], v[10:11], off nt
.LBB0_90:
	s_or_b64 exec, exec, s[40:41]
	v_mov_b32_e32 v18, 0
	v_mov_b32_e32 v22, 0
	v_mov_b32_e32 v23, 0
	v_mov_b32_e32 v24, 0
	v_mov_b32_e32 v25, 0
	s_and_saveexec_b64 s[40:41], vcc
	s_cbranch_execz .LBB0_92
	v_lshl_add_u64 v[20:21], s[10:11], 2, v[72:73]
	global_load_dwordx4 v[22:25], v[20:21], off nt
.LBB0_92:
	s_or_b64 exec, exec, s[40:41]
	v_mov_b32_e32 v19, 0
	v_mov_b32_e32 v20, 0
	v_mov_b32_e32 v21, 0
	s_and_saveexec_b64 s[40:41], vcc
	s_cbranch_execz .LBB0_94
	v_lshl_add_u64 v[18:19], s[14:15], 2, v[72:73]
	global_load_dwordx4 v[18:21], v[18:19], off nt
.LBB0_94:
	s_or_b64 exec, exec, s[40:41]
	v_mov_b32_e32 v26, 0
	v_mov_b32_e32 v30, 0
	v_mov_b32_e32 v31, 0
	v_mov_b32_e32 v32, 0
	v_mov_b32_e32 v33, 0
	s_and_saveexec_b64 s[40:41], vcc
	s_cbranch_execz .LBB0_96
	v_lshl_add_u64 v[28:29], s[16:17], 2, v[72:73]
	global_load_dwordx4 v[30:33], v[28:29], off nt
.LBB0_96:
	s_or_b64 exec, exec, s[40:41]
	v_mov_b32_e32 v27, 0
	v_mov_b32_e32 v28, 0
	v_mov_b32_e32 v29, 0
	s_and_saveexec_b64 s[40:41], vcc
	s_cbranch_execz .LBB0_98
	v_lshl_add_u64 v[26:27], s[18:19], 2, v[72:73]
	global_load_dwordx4 v[26:29], v[26:27], off nt
.LBB0_98:
	s_or_b64 exec, exec, s[40:41]
	v_mov_b32_e32 v34, 0
	v_mov_b32_e32 v38, 0
	v_mov_b32_e32 v39, 0
	v_mov_b32_e32 v40, 0
	v_mov_b32_e32 v41, 0
	s_and_saveexec_b64 s[40:41], vcc
	s_cbranch_execz .LBB0_100
	v_lshl_add_u64 v[36:37], s[20:21], 2, v[72:73]
	global_load_dwordx4 v[38:41], v[36:37], off nt
.LBB0_100:
	s_or_b64 exec, exec, s[40:41]
	v_mov_b32_e32 v35, 0
	v_mov_b32_e32 v36, 0
	v_mov_b32_e32 v37, 0
	s_and_saveexec_b64 s[40:41], vcc
	s_cbranch_execz .LBB0_102
	v_lshl_add_u64 v[34:35], s[22:23], 2, v[72:73]
	global_load_dwordx4 v[34:37], v[34:35], off nt
.LBB0_102:
	s_or_b64 exec, exec, s[40:41]
	v_mov_b32_e32 v42, 0
	v_mov_b32_e32 v46, 0
	v_mov_b32_e32 v47, 0
	v_mov_b32_e32 v48, 0
	v_mov_b32_e32 v49, 0
	s_and_saveexec_b64 s[40:41], vcc
	s_cbranch_execz .LBB0_104
	v_lshl_add_u64 v[44:45], s[24:25], 2, v[72:73]
	global_load_dwordx4 v[46:49], v[44:45], off nt
.LBB0_104:
	s_or_b64 exec, exec, s[40:41]
	v_mov_b32_e32 v43, 0
	v_mov_b32_e32 v44, 0
	v_mov_b32_e32 v45, 0
	s_and_saveexec_b64 s[40:41], vcc
	s_cbranch_execz .LBB0_106
	v_lshl_add_u64 v[42:43], s[26:27], 2, v[72:73]
	global_load_dwordx4 v[42:45], v[42:43], off nt
.LBB0_106:
	s_or_b64 exec, exec, s[40:41]
	v_mov_b32_e32 v50, 0
	v_mov_b32_e32 v54, 0
	v_mov_b32_e32 v55, 0
	v_mov_b32_e32 v56, 0
	v_mov_b32_e32 v57, 0
	s_and_saveexec_b64 s[40:41], vcc
	s_cbranch_execz .LBB0_108
	v_lshl_add_u64 v[52:53], s[28:29], 2, v[72:73]
	global_load_dwordx4 v[54:57], v[52:53], off nt
.LBB0_108:
	s_or_b64 exec, exec, s[40:41]
	v_mov_b32_e32 v51, 0
	v_mov_b32_e32 v52, 0
	v_mov_b32_e32 v53, 0
	s_and_saveexec_b64 s[40:41], vcc
	s_cbranch_execz .LBB0_110
	v_lshl_add_u64 v[50:51], s[30:31], 2, v[72:73]
	global_load_dwordx4 v[50:53], v[50:51], off nt
.LBB0_110:
	s_or_b64 exec, exec, s[40:41]
	v_mov_b32_e32 v58, 0
	v_mov_b32_e32 v62, 0
	v_mov_b32_e32 v63, 0
	v_mov_b32_e32 v64, 0
	v_mov_b32_e32 v65, 0
	s_and_saveexec_b64 s[40:41], vcc
	s_cbranch_execz .LBB0_112
	v_lshl_add_u64 v[60:61], s[34:35], 2, v[72:73]
	global_load_dwordx4 v[62:65], v[60:61], off nt
.LBB0_112:
	s_or_b64 exec, exec, s[40:41]
	v_mov_b32_e32 v59, 0
	v_mov_b32_e32 v60, 0
	v_mov_b32_e32 v61, 0
	s_and_saveexec_b64 s[40:41], vcc
	s_cbranch_execz .LBB0_57
	v_lshl_add_u64 v[58:59], s[36:37], 2, v[72:73]
	global_load_dwordx4 v[58:61], v[58:59], off nt
	s_branch .LBB0_57

.LBB0_116:
	global_load_dwordx4 v[10:13], v[6:7], off nt
	v_lshl_add_u64 v[14:15], v[6:7], 0, s[18:19]
	v_add_u32_e32 v18, s22, v8
	v_add_u32_e32 v20, s23, v8
	v_add_u32_e32 v22, s24, v8
	v_add_u32_e32 v24, s25, v8
	v_add_u32_e32 v26, s26, v8
	v_add_u32_e32 v28, s27, v8
	global_load_dwordx4 v[14:17], v[14:15], off nt
	v_ashrrev_i32_e32 v19, 31, v18
	v_ashrrev_i32_e32 v21, 31, v20
	v_ashrrev_i32_e32 v23, 31, v22
	v_ashrrev_i32_e32 v25, 31, v24
	v_ashrrev_i32_e32 v27, 31, v26
	v_ashrrev_i32_e32 v29, 31, v28
	v_lshl_add_u64 v[30:31], v[18:19], 4, s[6:7]
	v_lshl_add_u64 v[32:33], v[20:21], 4, s[6:7]
	v_lshl_add_u64 v[34:35], v[22:23], 4, s[6:7]
	v_lshl_add_u64 v[36:37], v[24:25], 4, s[6:7]
	v_lshl_add_u64 v[38:39], v[26:27], 4, s[6:7]
	v_lshl_add_u64 v[40:41], v[28:29], 4, s[6:7]
	v_lshl_add_u64 v[44:45], v[18:19], 3, s[8:9]
	v_lshl_add_u64 v[46:47], v[20:21], 3, s[8:9]
	v_lshl_add_u64 v[48:49], v[22:23], 3, s[8:9]
	v_lshl_add_u64 v[50:51], v[24:25], 3, s[8:9]
	v_lshl_add_u64 v[52:53], v[26:27], 3, s[8:9]
	v_lshl_add_u64 v[54:55], v[28:29], 3, s[8:9]
	global_load_dwordx4 v[18:21], v[30:31], off nt
	global_load_dwordx4 v[22:25], v[32:33], off nt
	global_load_dwordx4 v[26:29], v[34:35], off nt
	s_nop 0
	global_load_dwordx4 v[30:33], v[36:37], off nt
	s_nop 0
	global_load_dwordx4 v[34:37], v[38:39], off nt
	s_nop 0
	global_load_dwordx4 v[38:41], v[40:41], off nt
	v_lshl_add_u64 v[42:43], v[4:5], 0, s[14:15]
	v_add_u32_e32 v8, s10, v8
	v_cmp_lt_i32_e32 vcc, s29, v8
	v_lshl_add_u64 v[6:7], v[6:7], 0, s[20:21]
	s_or_b64 s[0:1], vcc, s[0:1]
	s_waitcnt vmcnt(7)
	v_bfe_u32 v9, v10, 16, 1
	v_bfe_u32 v56, v11, 16, 1
	v_bfe_u32 v57, v12, 16, 1
	v_bfe_u32 v58, v13, 16, 1
	v_add3_u32 v9, v10, v9, s11
	v_add3_u32 v10, v11, v56, s11
	v_add3_u32 v11, v12, v57, s11
	v_add3_u32 v12, v13, v58, s11
	s_waitcnt vmcnt(6)
	v_bfe_u32 v13, v14, 16, 1
	v_bfe_u32 v56, v15, 16, 1
	v_bfe_u32 v57, v16, 16, 1
	v_bfe_u32 v58, v17, 16, 1
	v_lshrrev_b32_e32 v9, 16, v9
	v_lshrrev_b32_e32 v11, 16, v11
	v_add3_u32 v13, v14, v13, s11
	v_add3_u32 v14, v15, v56, s11
	v_add3_u32 v15, v16, v57, s11
	v_add3_u32 v16, v17, v58, s11
	v_and_or_b32 v10, v10, s28, v9
	v_and_or_b32 v11, v12, s28, v11
	v_lshrrev_b32_e32 v9, 16, v13
	v_lshrrev_b32_e32 v12, 16, v15
	s_waitcnt vmcnt(5)
	v_bfe_u32 v13, v18, 16, 1
	v_bfe_u32 v17, v20, 16, 1
	v_bfe_u32 v15, v19, 16, 1
	v_bfe_u32 v56, v21, 16, 1
	s_waitcnt vmcnt(4)
	v_bfe_u32 v57, v22, 16, 1
	v_bfe_u32 v58, v23, 16, 1
	v_bfe_u32 v59, v24, 16, 1
	v_bfe_u32 v60, v25, 16, 1
	s_waitcnt vmcnt(3)
	v_bfe_u32 v61, v26, 16, 1
	v_bfe_u32 v62, v27, 16, 1
	v_bfe_u32 v63, v28, 16, 1
	v_bfe_u32 v64, v29, 16, 1
	s_waitcnt vmcnt(2)
	v_bfe_u32 v65, v30, 16, 1
	v_bfe_u32 v66, v31, 16, 1
	v_bfe_u32 v67, v32, 16, 1
	v_bfe_u32 v68, v33, 16, 1
	s_waitcnt vmcnt(1)
	v_bfe_u32 v69, v34, 16, 1
	v_bfe_u32 v71, v36, 16, 1
	s_waitcnt vmcnt(0)
	v_bfe_u32 v73, v38, 16, 1
	v_bfe_u32 v75, v40, 16, 1
	global_store_dwordx2 v[4:5], v[10:11], off sc1
	v_and_or_b32 v10, v14, s28, v9
	v_and_or_b32 v11, v16, s28, v12
	v_add3_u32 v9, v18, v13, s11
	v_add3_u32 v13, v20, v17, s11
	v_bfe_u32 v70, v35, 16, 1
	v_bfe_u32 v72, v37, 16, 1
	v_bfe_u32 v74, v39, 16, 1
	v_bfe_u32 v76, v41, 16, 1
	v_add3_u32 v12, v19, v15, s11
	v_add3_u32 v14, v21, v56, s11
	v_add3_u32 v15, v22, v57, s11
	v_add3_u32 v16, v23, v58, s11
	v_add3_u32 v17, v24, v59, s11
	v_add3_u32 v18, v25, v60, s11
	v_add3_u32 v19, v26, v61, s11
	v_add3_u32 v20, v27, v62, s11
	v_add3_u32 v21, v28, v63, s11
	v_add3_u32 v22, v29, v64, s11
	v_add3_u32 v23, v30, v65, s11
	v_add3_u32 v24, v31, v66, s11
	v_add3_u32 v25, v32, v67, s11
	v_add3_u32 v26, v33, v68, s11
	v_add3_u32 v27, v34, v69, s11
	v_add3_u32 v29, v36, v71, s11
	v_add3_u32 v31, v38, v73, s11
	v_add3_u32 v33, v40, v75, s11
	global_store_dwordx2 v[42:43], v[10:11], off sc1
	v_lshrrev_b32_e32 v9, 16, v9
	v_lshrrev_b32_e32 v11, 16, v13
	v_add3_u32 v28, v35, v70, s11
	v_add3_u32 v30, v37, v72, s11
	v_add3_u32 v32, v39, v74, s11
	v_add3_u32 v34, v41, v76, s11
	v_lshl_add_u64 v[4:5], v[4:5], 0, s[16:17]
	v_lshrrev_b32_e32 v13, 16, v15
	v_lshrrev_b32_e32 v15, 16, v17
	v_lshrrev_b32_e32 v17, 16, v19
	v_lshrrev_b32_e32 v19, 16, v21
	v_lshrrev_b32_e32 v21, 16, v23
	v_lshrrev_b32_e32 v23, 16, v25
	v_lshrrev_b32_e32 v25, 16, v27
	v_lshrrev_b32_e32 v27, 16, v29
	v_lshrrev_b32_e32 v29, 16, v31
	v_lshrrev_b32_e32 v31, 16, v33
	v_and_or_b32 v10, v12, s28, v9
	v_and_or_b32 v11, v14, s28, v11
	v_and_or_b32 v12, v16, s28, v13
	v_and_or_b32 v13, v18, s28, v15
	v_and_or_b32 v14, v20, s28, v17
	v_and_or_b32 v15, v22, s28, v19
	v_and_or_b32 v16, v24, s28, v21
	v_and_or_b32 v17, v26, s28, v23
	v_and_or_b32 v18, v28, s28, v25
	v_and_or_b32 v19, v30, s28, v27
	v_and_or_b32 v20, v32, s28, v29
	v_and_or_b32 v21, v34, s28, v31
	global_store_dwordx2 v[44:45], v[10:11], off sc1
	global_store_dwordx2 v[46:47], v[12:13], off sc1
	global_store_dwordx2 v[48:49], v[14:15], off sc1
	global_store_dwordx2 v[50:51], v[16:17], off sc1
	global_store_dwordx2 v[52:53], v[18:19], off sc1
	global_store_dwordx2 v[54:55], v[20:21], off sc1
	s_andn2_b64 exec, exec, s[0:1]
	s_cbranch_execnz .LBB0_116
.LBB0_117:
	s_or_b64 exec, exec, s[4:5]
	v_readlane_b32 s0, v253, 39
	s_mov_b64 s[4:5], 0
	s_mov_b64 s[6:7], 0
	v_readlane_b32 s1, v253, 40
	v_cmp_gt_i32_e32 vcc, s0, v2
	s_and_saveexec_b64 s[0:1], vcc
	s_cbranch_execz .LBB0_119
	s_add_u32 s4, s74, s4
	v_readlane_b32 s16, v253, 6
	s_addc_u32 s5, s75, s5
	v_readlane_b32 s17, v253, 7
	s_add_u32 s4, s4, 0xb00000
	v_readlane_b32 s18, v253, 8
	v_readlane_b32 s19, v253, 9
	s_mov_b64 s[8:9], s[16:17]
	s_addc_u32 s5, s5, 0
	s_lshl_b64 s[6:7], s[6:7], 2
	s_mov_b64 s[10:11], s[18:19]
	v_readlane_b32 s8, v253, 39
	s_add_u32 s6, s10, s6
	s_mov_b32 s10, s8
	s_addc_u32 s7, s11, s7
	s_ashr_i32 s11, s8, 31
	s_add_i32 s8, s10, s10
	v_add_u32_e32 v20, s8, v2
	v_ashrrev_i32_e32 v21, 31, v20
	v_lshl_add_u64 v[8:9], v[2:3], 4, s[6:7]
	v_lshl_add_u64 v[12:13], v[20:21], 4, s[6:7]
	global_load_dwordx4 v[4:7], v[8:9], off nt
	v_add_u32_e32 v22, s10, v20
	global_load_dwordx4 v[12:15], v[12:13], off nt
	v_lshl_add_u64 v[8:9], s[10:11], 4, v[8:9]
	global_load_dwordx4 v[8:11], v[8:9], off nt
	v_ashrrev_i32_e32 v23, 31, v22
	v_lshl_add_u64 v[16:17], v[22:23], 4, s[6:7]
	global_load_dwordx4 v[16:19], v[16:17], off nt
	s_movk_i32 s6, 0x7fff
	s_mov_b32 s7, 0xffff0000
	v_lshl_add_u64 v[24:25], v[2:3], 3, s[4:5]
	v_readlane_b32 s9, v253, 40
	s_mov_b32 s8, s10
	v_lshl_add_u64 v[26:27], s[10:11], 3, v[24:25]
	v_readlane_b32 s20, v253, 10
	v_readlane_b32 s21, v253, 11
	v_readlane_b32 s22, v253, 12
	v_readlane_b32 s23, v253, 13
	v_readlane_b32 s24, v253, 14
	v_readlane_b32 s25, v253, 15
	v_readlane_b32 s26, v253, 16
	v_readlane_b32 s27, v253, 17
	v_readlane_b32 s28, v253, 18
	v_readlane_b32 s29, v253, 19
	v_readlane_b32 s30, v253, 20
	v_readlane_b32 s31, v253, 21
	v_writelane_b32 v253, s8, 39
	v_lshl_add_u64 v[20:21], v[20:21], 3, s[4:5]
	s_waitcnt vmcnt(3)
	v_bfe_u32 v28, v4, 16, 1
	v_bfe_u32 v30, v6, 16, 1
	v_bfe_u32 v29, v5, 16, 1
	v_bfe_u32 v31, v7, 16, 1
	v_add3_u32 v4, v4, v28, s6
	v_add3_u32 v6, v6, v30, s6
	s_waitcnt vmcnt(1)
	v_bfe_u32 v28, v8, 16, 1
	v_bfe_u32 v30, v10, 16, 1
	v_add3_u32 v5, v5, v29, s6
	v_add3_u32 v7, v7, v31, s6
	v_bfe_u32 v29, v9, 16, 1
	v_bfe_u32 v31, v11, 16, 1
	v_lshrrev_b32_e32 v4, 16, v4
	v_lshrrev_b32_e32 v6, 16, v6
	v_add3_u32 v8, v8, v28, s6
	v_add3_u32 v10, v10, v30, s6
	v_bfe_u32 v28, v12, 16, 1
	v_bfe_u32 v30, v14, 16, 1
	v_add3_u32 v9, v9, v29, s6
	v_add3_u32 v11, v11, v31, s6
	v_bfe_u32 v29, v13, 16, 1
	v_bfe_u32 v31, v15, 16, 1
	v_and_or_b32 v4, v5, s7, v4
	v_and_or_b32 v5, v7, s7, v6
	v_lshrrev_b32_e32 v6, 16, v8
	v_lshrrev_b32_e32 v7, 16, v10
	v_add3_u32 v8, v12, v28, s6
	v_add3_u32 v12, v14, v30, s6
	s_waitcnt vmcnt(0)
	v_bfe_u32 v14, v16, 16, 1
	v_bfe_u32 v28, v18, 16, 1
	v_add3_u32 v10, v13, v29, s6
	v_add3_u32 v13, v15, v31, s6
	v_bfe_u32 v15, v17, 16, 1
	v_bfe_u32 v29, v19, 16, 1
	global_store_dwordx2 v[24:25], v[4:5], off sc1
	v_and_or_b32 v4, v9, s7, v6
	v_and_or_b32 v5, v11, s7, v7
	v_lshrrev_b32_e32 v6, 16, v8
	v_lshrrev_b32_e32 v7, 16, v12
	v_add3_u32 v8, v16, v14, s6
	v_add3_u32 v11, v18, v28, s6
	v_add3_u32 v9, v17, v15, s6
	v_add3_u32 v12, v19, v29, s6
	global_store_dwordx2 v[26:27], v[4:5], off sc1
	v_and_or_b32 v4, v10, s7, v6
	v_and_or_b32 v5, v13, s7, v7
	v_lshrrev_b32_e32 v6, 16, v8
	v_lshrrev_b32_e32 v7, 16, v11
	v_writelane_b32 v253, s9, 40
	global_store_dwordx2 v[20:21], v[4:5], off sc1
	v_and_or_b32 v4, v9, s7, v6
	v_and_or_b32 v5, v12, s7, v7
	v_lshl_add_u64 v[6:7], v[22:23], 3, s[4:5]
	global_store_dwordx2 v[6:7], v[4:5], off sc1
